# v14 + convert_weights with two items (68 loads) in flight per wave: second register buffer, loads for item k+2 issued while item k is transposed and stored
# speedup vs baseline: 1.0104x; 1.0092x over previous
; #define LAS __attribute__((address_space(3)))
; __device__ __forceinline__ int opaque_tid(int wv) { int l; asm volatile("v_mbcnt_lo_u32_b32 %0, -1, 0\n\tv_mbcnt_hi_u32_b32 %0, -1, %0" : "=v"(l)); return (wv << 6) | l; }
; template <class Tp> __device__ __forceinline__ Tp* opaque_ptr(Tp* p) { asm volatile("" : "+s"(p)); return p; }
; __device__ __forceinline__ void convert_weights(int wv, const Args& a, int l, LAS unsigned char* lds) {
;     const int tid = opaque_tid(wv), lane = tid & 63, wave = tid >> 6;
;     LAS float* scr = (LAS float*)(lds + wave * 16384);
;     unsigned char* ws = opaque_ptr(a.ws);
;     const int gw = blockIdx.x * 8 + wave, NGW = NWG * 8;
;     constexpr int I1 = 16 * 176, I1O = 44 * 32, IIN = 16 * 336, IA = 16 * 32, IB = 8 * 32, IO = 16 * 32;
;     constexpr int NIT = 2 * I1 + 2 * I1O + IIN + IA + IB + IO;
;     for (int it = gw; it < NIT; it += NGW) {
;         int r = it;
;         if (r < 2 * I1) {
;             const int which = r / I1; r -= which * I1;
;             const float* W = (which ? a.in[14] : a.in[2]) + (size_t)l * DM * 2 * DFF; const float* gn = (which ? a.in[13] : a.in[1]) + l * DM;
;             bf16_t* WT = (bf16_t*)(ws + (which ? W_2T : W_1T));
;             const int kb = r / 176, nb = r % 176, n0 = nb * 32, pn = n0 >> 8, bj = (n0 >> 7) & 1, i0 = n0 & 127;
;             transpose_item(W, DM, 2 * DFF, gn, WT, n0, bj * DFF + 128 * pn + i0, kb * 64, scr, lane); continue; }
.LBB0_41:
	v_readlane_b32 s0, v252, 4
	v_readlane_b32 s1, v252, 5
	s_mov_b64 exec, -1
	s_load_dwordx2 s[26:27], s[0:1], 0x88
	v_readlane_b32 s4, v252, 3
	v_readlane_b32 s5, v252, 1
	v_mbcnt_lo_u32_b32 v4, -1, 0
	v_mbcnt_hi_u32_b32 v4, -1, v4
	s_lshr_b32 s5, s5, 6
	s_add_u32 s4, s4, s5
	s_mov_b32 s30, s4
	s_lshl_b32 s6, s5, 14
	v_and_b32_e32 v5, 31, v4
	v_lshrrev_b32_e32 v6, 5, v4
	v_lshlrev_b32_e32 v7, 2, v5
	v_and_b32_e32 v8, 7, v4
	v_lshrrev_b32_e32 v9, 3, v4
	v_mad_u32_u24 v10, v6, 33, v5
	v_lshl_add_u32 v10, v10, 2, s6
	v_mul_u32_u24_e32 v11, 0x108, v8
	v_add_u32_e32 v11, v11, v9
	v_lshl_add_u32 v11, v11, 2, s6
	v_lshlrev_b32_e32 v12, 5, v8
	v_lshlrev_b32_e32 v13, 4, v8
	s_waitcnt lgkmcnt(0)
	s_mov_b32 s22, s4
	s_cmpk_lt_u32 s22, 0x1600
	s_cbranch_scc0 .Lcvd1_c2
	s_mov_b32 s40, 0x600000
	s_mov_b32 s29, 0x3080000
	s_cmpk_ge_u32 s22, 0xb00
	s_cselect_b32 s37, 0x70, 16
	s_cselect_b32 s36, 0x68, 8
	s_cselect_b32 s40, s29, s40
	s_cselect_b32 s29, 0xb00, 0
	s_sub_u32 s22, s22, s29
	s_movk_i32 s41, 0x1600
	s_movk_i32 s42, 0x400
	s_mov_b32 s39, 0x1600000
	s_mov_b32 s38, 1
	s_and_b32 s28, s22, 15
	s_bfe_u32 s23, s22, 0x40004
	s_lshr_b32 s29, s22, 8
	s_lshl_b32 s29, s29, 4
	s_add_u32 s28, s28, s29
	s_lshl_b32 s45, s28, 5
	s_lshr_b32 s29, s45, 8
	s_lshl_b32 s43, s29, 7
	s_and_b32 s29, s45, 0x7f
	s_add_u32 s43, s43, s29
	s_bitcmp1_b32 s45, 7
	s_cselect_b32 s29, 0xb00, 0
	s_add_u32 s43, s43, s29
	s_branch .Lcvd1_done

; #define LAS __attribute__((address_space(3)))
; __device__ __forceinline__ void transpose_item(const float* W, int K, int Nsrc, const float* gain, bf16_t* WT, int dst_row0, int src_col0, int k0, LAS float* scr, int lane) {
; #pragma unroll 8
;     for (int i = 0; i < 32; ++i) { const int kk = 2 * i + (lane >> 5); const float g = gain ? gain[k0 + kk] : 1.f; scr[kk * 33 + (lane & 31)] = W[(size_t)(k0 + kk) * Nsrc + src_col0 + (lane & 31)] * g; }
; __device__ __forceinline__ void convert_weights(int wv, const Args& a, int l, LAS unsigned char* lds) {
;     ...
;     for (int it = gw; it < NIT; it += NGW) {
;         int r = it;
;         if (r < 2 * I1) {
;             const int which = r / I1; r -= which * I1;
;             const float* W = (which ? a.in[14] : a.in[2]) + (size_t)l * DM * 2 * DFF; const float* gn = (which ? a.in[13] : a.in[1]) + l * DM;
;             bf16_t* WT = (bf16_t*)(ws + (which ? W_2T : W_1T));
;             const int kb = r / 176, nb = r % 176, n0 = nb * 32, pn = n0 >> 8, bj = (n0 >> 7) & 1, i0 = n0 & 127;
;             transpose_item(W, DM, 2 * DFF, gn, WT, n0, bj * DFF + 128 * pn + i0, kb * 64, scr, lane); continue; }
.Lcvd1_hasg:
	global_load_dword v72, v14, s[8:9]
	s_add_u32 s8, s8, s10
	s_addc_u32 s9, s9, 0
	global_load_dword v73, v14, s[8:9]
	s_add_u32 s8, s8, s10
	s_addc_u32 s9, s9, 0
	global_load_dword v74, v14, s[8:9]
	s_add_u32 s8, s8, s10
	s_addc_u32 s9, s9, 0
	global_load_dword v75, v14, s[8:9]
	s_add_u32 s8, s8, s10
	s_addc_u32 s9, s9, 0
	global_load_dword v76, v14, s[8:9]
	s_add_u32 s8, s8, s10
	s_addc_u32 s9, s9, 0
	global_load_dword v77, v14, s[8:9]
	s_add_u32 s8, s8, s10
	s_addc_u32 s9, s9, 0
	global_load_dword v78, v14, s[8:9]
	s_add_u32 s8, s8, s10
	s_addc_u32 s9, s9, 0
	global_load_dword v79, v14, s[8:9]
	s_add_u32 s8, s8, s10
	s_addc_u32 s9, s9, 0
	global_load_dword v80, v14, s[8:9]
	s_add_u32 s8, s8, s10
	s_addc_u32 s9, s9, 0
	global_load_dword v81, v14, s[8:9]
	s_add_u32 s8, s8, s10
	s_addc_u32 s9, s9, 0
	global_load_dword v82, v14, s[8:9]
	s_add_u32 s8, s8, s10
	s_addc_u32 s9, s9, 0
	global_load_dword v83, v14, s[8:9]
	s_add_u32 s8, s8, s10
	s_addc_u32 s9, s9, 0
	global_load_dword v84, v14, s[8:9]
	s_add_u32 s8, s8, s10
	s_addc_u32 s9, s9, 0
	global_load_dword v85, v14, s[8:9]
	s_add_u32 s8, s8, s10
	s_addc_u32 s9, s9, 0
	global_load_dword v86, v14, s[8:9]
	s_add_u32 s8, s8, s10
	s_addc_u32 s9, s9, 0
	global_load_dword v87, v14, s[8:9]
	s_add_u32 s8, s8, s10
	s_addc_u32 s9, s9, 0
	global_load_dword v88, v14, s[8:9]
	s_add_u32 s8, s8, s10
	s_addc_u32 s9, s9, 0
	global_load_dword v89, v14, s[8:9]
	s_add_u32 s8, s8, s10
	s_addc_u32 s9, s9, 0
	global_load_dword v90, v14, s[8:9]
	s_add_u32 s8, s8, s10
	s_addc_u32 s9, s9, 0
	global_load_dword v91, v14, s[8:9]
	s_add_u32 s8, s8, s10
	s_addc_u32 s9, s9, 0
	global_load_dword v92, v14, s[8:9]
	s_add_u32 s8, s8, s10
	s_addc_u32 s9, s9, 0
	global_load_dword v93, v14, s[8:9]
	s_add_u32 s8, s8, s10
	s_addc_u32 s9, s9, 0
	global_load_dword v94, v14, s[8:9]
	s_add_u32 s8, s8, s10
	s_addc_u32 s9, s9, 0
	global_load_dword v95, v14, s[8:9]
	s_add_u32 s8, s8, s10
	s_addc_u32 s9, s9, 0
	global_load_dword v96, v14, s[8:9]
	s_add_u32 s8, s8, s10
	s_addc_u32 s9, s9, 0
	global_load_dword v97, v14, s[8:9]
	s_add_u32 s8, s8, s10
	s_addc_u32 s9, s9, 0
	global_load_dword v98, v14, s[8:9]
	s_add_u32 s8, s8, s10
	s_addc_u32 s9, s9, 0
	global_load_dword v99, v14, s[8:9]
	s_add_u32 s8, s8, s10
	s_addc_u32 s9, s9, 0
	global_load_dword v100, v14, s[8:9]
	s_add_u32 s8, s8, s10
	s_addc_u32 s9, s9, 0
	global_load_dword v101, v14, s[8:9]
	s_add_u32 s8, s8, s10
	s_addc_u32 s9, s9, 0
	global_load_dword v102, v14, s[8:9]
	s_add_u32 s8, s8, s10
	s_addc_u32 s9, s9, 0
	global_load_dword v103, v14, s[8:9]
	global_load_dwordx4 v[20:23], v12, s[12:13]
	global_load_dwordx4 v[24:27], v12, s[12:13] offset:16
	s_mov_b64 s[18:19], s[14:15]
	s_mov_b32 s20, s16
	s_mov_b32 s21, s38
	v_mov_b32_e32 v16, v15
	s_add_u32 s4, s30, 0x800
	s_cmpk_lt_u32 s4, 0x3b00
	s_cbranch_scc0 .Lcv_bodyA
	s_mov_b32 s22, s4
	s_cmpk_lt_u32 s22, 0x1600
	s_cbranch_scc0 .Lcvd2_c2
	s_mov_b32 s40, 0x600000
	s_mov_b32 s29, 0x3080000
	s_cmpk_ge_u32 s22, 0xb00
	s_cselect_b32 s37, 0x70, 16
	s_cselect_b32 s36, 0x68, 8
	s_cselect_b32 s40, s29, s40
	s_cselect_b32 s29, 0xb00, 0
	s_sub_u32 s22, s22, s29
	s_movk_i32 s41, 0x1600
	s_movk_i32 s42, 0x400
	s_mov_b32 s39, 0x1600000
	s_mov_b32 s38, 1
	s_and_b32 s28, s22, 15
	s_bfe_u32 s23, s22, 0x40004
	s_lshr_b32 s29, s22, 8
	s_lshl_b32 s29, s29, 4
	s_add_u32 s28, s28, s29
	s_lshl_b32 s45, s28, 5
	s_lshr_b32 s29, s45, 8
	s_lshl_b32 s43, s29, 7
	s_and_b32 s29, s45, 0x7f
	s_add_u32 s43, s43, s29
	s_bitcmp1_b32 s45, 7
	s_cselect_b32 s29, 0xb00, 0
	s_add_u32 s43, s43, s29
	s_branch .Lcvd2_done

; #define LAS __attribute__((address_space(3)))
; __device__ __forceinline__ void transpose_item(const float* W, int K, int Nsrc, const float* gain, bf16_t* WT, int dst_row0, int src_col0, int k0, LAS float* scr, int lane) {
; #pragma unroll 8
;     for (int i = 0; i < 32; ++i) { const int kk = 2 * i + (lane >> 5); const float g = gain ? gain[k0 + kk] : 1.f; scr[kk * 33 + (lane & 31)] = W[(size_t)(k0 + kk) * Nsrc + src_col0 + (lane & 31)] * g; }
;     asm volatile("s_waitcnt lgkmcnt(0)" ::: "memory");
; __device__ __forceinline__ void convert_weights(int wv, const Args& a, int l, LAS unsigned char* lds) {
;     ...
;     for (int it = gw; it < NIT; it += NGW) {
;         int r = it;
.Lcvd2_hasg:
	global_load_dword v152, v14, s[8:9]
	s_add_u32 s8, s8, s10
	s_addc_u32 s9, s9, 0
	global_load_dword v153, v14, s[8:9]
	s_add_u32 s8, s8, s10
	s_addc_u32 s9, s9, 0
	global_load_dword v154, v14, s[8:9]
	s_add_u32 s8, s8, s10
	s_addc_u32 s9, s9, 0
	global_load_dword v155, v14, s[8:9]
	s_add_u32 s8, s8, s10
	s_addc_u32 s9, s9, 0
	global_load_dword v156, v14, s[8:9]
	s_add_u32 s8, s8, s10
	s_addc_u32 s9, s9, 0
	global_load_dword v157, v14, s[8:9]
	s_add_u32 s8, s8, s10
	s_addc_u32 s9, s9, 0
	global_load_dword v158, v14, s[8:9]
	s_add_u32 s8, s8, s10
	s_addc_u32 s9, s9, 0
	global_load_dword v159, v14, s[8:9]
	s_add_u32 s8, s8, s10
	s_addc_u32 s9, s9, 0
	global_load_dword v160, v14, s[8:9]
	s_add_u32 s8, s8, s10
	s_addc_u32 s9, s9, 0
	global_load_dword v161, v14, s[8:9]
	s_add_u32 s8, s8, s10
	s_addc_u32 s9, s9, 0
	global_load_dword v162, v14, s[8:9]
	s_add_u32 s8, s8, s10
	s_addc_u32 s9, s9, 0
	global_load_dword v163, v14, s[8:9]
	s_add_u32 s8, s8, s10
	s_addc_u32 s9, s9, 0
	global_load_dword v164, v14, s[8:9]
	s_add_u32 s8, s8, s10
	s_addc_u32 s9, s9, 0
	global_load_dword v165, v14, s[8:9]
	s_add_u32 s8, s8, s10
	s_addc_u32 s9, s9, 0
	global_load_dword v166, v14, s[8:9]
	s_add_u32 s8, s8, s10
	s_addc_u32 s9, s9, 0
	global_load_dword v167, v14, s[8:9]
	s_add_u32 s8, s8, s10
	s_addc_u32 s9, s9, 0
	global_load_dword v168, v14, s[8:9]
	s_add_u32 s8, s8, s10
	s_addc_u32 s9, s9, 0
	global_load_dword v169, v14, s[8:9]
	s_add_u32 s8, s8, s10
	s_addc_u32 s9, s9, 0
	global_load_dword v170, v14, s[8:9]
	s_add_u32 s8, s8, s10
	s_addc_u32 s9, s9, 0
	global_load_dword v171, v14, s[8:9]
	s_add_u32 s8, s8, s10
	s_addc_u32 s9, s9, 0
	global_load_dword v172, v14, s[8:9]
	s_add_u32 s8, s8, s10
	s_addc_u32 s9, s9, 0
	global_load_dword v173, v14, s[8:9]
	s_add_u32 s8, s8, s10
	s_addc_u32 s9, s9, 0
	global_load_dword v174, v14, s[8:9]
	s_add_u32 s8, s8, s10
	s_addc_u32 s9, s9, 0
	global_load_dword v175, v14, s[8:9]
	s_add_u32 s8, s8, s10
	s_addc_u32 s9, s9, 0
	global_load_dword v176, v14, s[8:9]
	s_add_u32 s8, s8, s10
	s_addc_u32 s9, s9, 0
	global_load_dword v177, v14, s[8:9]
	s_add_u32 s8, s8, s10
	s_addc_u32 s9, s9, 0
	global_load_dword v178, v14, s[8:9]
	s_add_u32 s8, s8, s10
	s_addc_u32 s9, s9, 0
	global_load_dword v179, v14, s[8:9]
	s_add_u32 s8, s8, s10
	s_addc_u32 s9, s9, 0
	global_load_dword v180, v14, s[8:9]
	s_add_u32 s8, s8, s10
	s_addc_u32 s9, s9, 0
	global_load_dword v181, v14, s[8:9]
	s_add_u32 s8, s8, s10
	s_addc_u32 s9, s9, 0
	global_load_dword v182, v14, s[8:9]
	s_add_u32 s8, s8, s10
	s_addc_u32 s9, s9, 0
	global_load_dword v183, v14, s[8:9]
	global_load_dwordx4 v[36:39], v12, s[12:13]
	global_load_dwordx4 v[40:43], v12, s[12:13] offset:16
	s_mov_b64 s[52:53], s[14:15]
	s_mov_b32 s58, s16
	s_mov_b32 s72, s38
	v_mov_b32_e32 v17, v15
.Lcv_bodyA:
	s_add_u32 s31, s30, 0x800
	s_cmpk_lt_u32 s31, 0x3b00
	s_cbranch_scc1 .Lcv_wA
	s_waitcnt vmcnt(0)
	s_branch .Lcv_wAd
.Lcv_wA:
	s_waitcnt vmcnt(34)

; __device__ __forceinline__ void convert_weights(int wv, const Args& a, int l, LAS unsigned char* lds) {
;     ...
;     for (int it = gw; it < NIT; it += NGW) {
;         int r = it;
;         if (r < 2 * I1) {
;             const int which = r / I1; r -= which * I1;
;             const float* W = (which ? a.in[14] : a.in[2]) + (size_t)l * DM * 2 * DFF; const float* gn = (which ? a.in[13] : a.in[1]) + l * DM;
;             bf16_t* WT = (bf16_t*)(ws + (which ? W_2T : W_1T));
;             const int kb = r / 176, nb = r % 176, n0 = nb * 32, pn = n0 >> 8, bj = (n0 >> 7) & 1, i0 = n0 & 127;
;             transpose_item(W, DM, 2 * DFF, gn, WT, n0, bj * DFF + 128 * pn + i0, kb * 64, scr, lane); continue; }
.Lcv_g2A:
	s_add_u32 s4, s30, 0x1000
	s_cmpk_lt_u32 s4, 0x3b00
	s_cbranch_scc0 .Lcv_nonextA
	s_mov_b32 s22, s4
	s_cmpk_lt_u32 s22, 0x1600
	s_cbranch_scc0 .Lcvd3_c2
	s_mov_b32 s40, 0x600000
	s_mov_b32 s29, 0x3080000
	s_cmpk_ge_u32 s22, 0xb00
	s_cselect_b32 s37, 0x70, 16
	s_cselect_b32 s36, 0x68, 8
	s_cselect_b32 s40, s29, s40
	s_cselect_b32 s29, 0xb00, 0
	s_sub_u32 s22, s22, s29
	s_movk_i32 s41, 0x1600
	s_movk_i32 s42, 0x400
	s_mov_b32 s39, 0x1600000
	s_mov_b32 s38, 1
	s_and_b32 s28, s22, 15
	s_bfe_u32 s23, s22, 0x40004
	s_lshr_b32 s29, s22, 8
	s_lshl_b32 s29, s29, 4
	s_add_u32 s28, s28, s29
	s_lshl_b32 s45, s28, 5
	s_lshr_b32 s29, s45, 8
	s_lshl_b32 s43, s29, 7
	s_and_b32 s29, s45, 0x7f
	s_add_u32 s43, s43, s29
	s_bitcmp1_b32 s45, 7
	s_cselect_b32 s29, 0xb00, 0
	s_add_u32 s43, s43, s29
	s_branch .Lcvd3_done

; #define LAS __attribute__((address_space(3)))
; __device__ __forceinline__ unsigned pk2(float lo, float hi) { f32x2 v = {lo, hi}; bf2_t b = __builtin_convertvector(v, bf2_t); return __builtin_bit_cast(unsigned, b); }
; __device__ __forceinline__ void transpose_item(const float* W, int K, int Nsrc, const float* gain, bf16_t* WT, int dst_row0, int src_col0, int k0, LAS float* scr, int lane) {
;     ...
;     const int c = lane & 7;
; #pragma unroll
;     for (int j = 0; j < 4; ++j) { const int n = (lane >> 3) + 8 * j; const LAS float* s = scr + (8 * c) * 33 + n;
;         u32x4 o; o.x = pk2(s[0 * 33], s[1 * 33]); o.y = pk2(s[2 * 33], s[3 * 33]); o.z = pk2(s[4 * 33], s[5 * 33]); o.w = pk2(s[6 * 33], s[7 * 33]);
;         *(u32x4*)(WT + (size_t)(dst_row0 + n) * K + k0 + 8 * c) = o; }
;     asm volatile("s_waitcnt lgkmcnt(0)" ::: "memory");
; __device__ __forceinline__ void convert_weights(int wv, const Args& a, int l, LAS unsigned char* lds) {
;     ...
;     for (int it = gw; it < NIT; it += NGW) {
.Lcv_nonextA:
	s_waitcnt lgkmcnt(0)
	ds_read_b32 v104, v11 offset:0
	ds_read_b32 v105, v11 offset:132
	ds_read_b32 v106, v11 offset:264
	ds_read_b32 v107, v11 offset:396
	ds_read_b32 v108, v11 offset:528
	ds_read_b32 v109, v11 offset:660
	ds_read_b32 v110, v11 offset:792
	ds_read_b32 v111, v11 offset:924
	ds_read_b32 v112, v11 offset:32
	ds_read_b32 v113, v11 offset:164
	ds_read_b32 v114, v11 offset:296
	ds_read_b32 v115, v11 offset:428
	ds_read_b32 v116, v11 offset:560
	ds_read_b32 v117, v11 offset:692
	ds_read_b32 v118, v11 offset:824
	ds_read_b32 v119, v11 offset:956
	s_waitcnt lgkmcnt(8)
	v_mul_f32_e32 v104, v104, v28
	v_mul_f32_e32 v105, v105, v29
	v_mul_f32_e32 v106, v106, v30
	v_mul_f32_e32 v107, v107, v31
	v_mul_f32_e32 v108, v108, v32
	v_mul_f32_e32 v109, v109, v33
	v_mul_f32_e32 v110, v110, v34
	v_mul_f32_e32 v111, v111, v35
	v_cvt_pk_bf16_f32 v136, v104, v105
	v_cvt_pk_bf16_f32 v137, v106, v107
	v_cvt_pk_bf16_f32 v138, v108, v109
	v_cvt_pk_bf16_f32 v139, v110, v111
	global_store_dwordx4 v16, v[136:139], s[18:19]
	s_add_u32 s18, s18, s20
	s_addc_u32 s19, s19, 0
	ds_read_b32 v120, v11 offset:64
	ds_read_b32 v121, v11 offset:196
	ds_read_b32 v122, v11 offset:328
	ds_read_b32 v123, v11 offset:460
	ds_read_b32 v124, v11 offset:592
	ds_read_b32 v125, v11 offset:724
	ds_read_b32 v126, v11 offset:856
	ds_read_b32 v127, v11 offset:988
	s_waitcnt lgkmcnt(8)
	v_mul_f32_e32 v112, v112, v28
	v_mul_f32_e32 v113, v113, v29
	v_mul_f32_e32 v114, v114, v30
	v_mul_f32_e32 v115, v115, v31
	v_mul_f32_e32 v116, v116, v32
	v_mul_f32_e32 v117, v117, v33
	v_mul_f32_e32 v118, v118, v34
	v_mul_f32_e32 v119, v119, v35
	v_cvt_pk_bf16_f32 v140, v112, v113
	v_cvt_pk_bf16_f32 v141, v114, v115
	v_cvt_pk_bf16_f32 v142, v116, v117
	v_cvt_pk_bf16_f32 v143, v118, v119
	global_store_dwordx4 v16, v[140:143], s[18:19]
	s_add_u32 s18, s18, s20
	s_addc_u32 s19, s19, 0
	ds_read_b32 v128, v11 offset:96
	ds_read_b32 v129, v11 offset:228
	ds_read_b32 v130, v11 offset:360
	ds_read_b32 v131, v11 offset:492
	ds_read_b32 v132, v11 offset:624
	ds_read_b32 v133, v11 offset:756
	ds_read_b32 v134, v11 offset:888
	ds_read_b32 v135, v11 offset:1020
	s_waitcnt lgkmcnt(8)
	v_mul_f32_e32 v120, v120, v28
	v_mul_f32_e32 v121, v121, v29
	v_mul_f32_e32 v122, v122, v30
	v_mul_f32_e32 v123, v123, v31
	v_mul_f32_e32 v124, v124, v32
	v_mul_f32_e32 v125, v125, v33
	v_mul_f32_e32 v126, v126, v34
	v_mul_f32_e32 v127, v127, v35
	v_cvt_pk_bf16_f32 v144, v120, v121
	v_cvt_pk_bf16_f32 v145, v122, v123
	v_cvt_pk_bf16_f32 v146, v124, v125
	v_cvt_pk_bf16_f32 v147, v126, v127
	global_store_dwordx4 v16, v[144:147], s[18:19]
	s_add_u32 s18, s18, s20
	s_addc_u32 s19, s19, 0
	s_waitcnt lgkmcnt(0)
	v_mul_f32_e32 v128, v128, v28
	v_mul_f32_e32 v129, v129, v29
	v_mul_f32_e32 v130, v130, v30
	v_mul_f32_e32 v131, v131, v31
	v_mul_f32_e32 v132, v132, v32
	v_mul_f32_e32 v133, v133, v33
	v_mul_f32_e32 v134, v134, v34
	v_mul_f32_e32 v135, v135, v35
	v_cvt_pk_bf16_f32 v148, v128, v129
	v_cvt_pk_bf16_f32 v149, v130, v131
	v_cvt_pk_bf16_f32 v150, v132, v133
	v_cvt_pk_bf16_f32 v151, v134, v135
	global_store_dwordx4 v16, v[148:151], s[18:19]
	s_mov_b64 s[18:19], s[14:15]
	s_mov_b32 s20, s16
	s_mov_b32 s21, s38
	v_mov_b32_e32 v16, v15
	s_add_u32 s30, s30, 0x800
	s_cmpk_lt_u32 s30, 0x3b00
	s_cbranch_scc1 .Lcv_bodyB
	s_branch .Lcv_end

; __device__ __forceinline__ void transpose_item(const float* W, int K, int Nsrc, const float* gain, bf16_t* WT, int dst_row0, int src_col0, int k0, LAS float* scr, int lane) {
;     ...
;     for (int i = 0; i < 32; ++i) { const int kk = 2 * i + (lane >> 5); const float g = gain ? gain[k0 + kk] : 1.f; scr[kk * 33 + (lane & 31)] = W[(size_t)(k0 + kk) * Nsrc + src_col0 + (lane & 31)] * g; }
.Lcv_wBd:
	ds_write_b32 v10, v152 offset:0
	ds_write_b32 v10, v153 offset:264
	ds_write_b32 v10, v154 offset:528
	ds_write_b32 v10, v155 offset:792
	ds_write_b32 v10, v156 offset:1056
	ds_write_b32 v10, v157 offset:1320
	ds_write_b32 v10, v158 offset:1584
	ds_write_b32 v10, v159 offset:1848
	ds_write_b32 v10, v160 offset:2112
	ds_write_b32 v10, v161 offset:2376
	ds_write_b32 v10, v162 offset:2640
	ds_write_b32 v10, v163 offset:2904
	ds_write_b32 v10, v164 offset:3168
	ds_write_b32 v10, v165 offset:3432
	ds_write_b32 v10, v166 offset:3696
	ds_write_b32 v10, v167 offset:3960
	ds_write_b32 v10, v168 offset:4224
	ds_write_b32 v10, v169 offset:4488
	ds_write_b32 v10, v170 offset:4752
	ds_write_b32 v10, v171 offset:5016
	ds_write_b32 v10, v172 offset:5280
	ds_write_b32 v10, v173 offset:5544
	ds_write_b32 v10, v174 offset:5808
	ds_write_b32 v10, v175 offset:6072
	ds_write_b32 v10, v176 offset:6336
	ds_write_b32 v10, v177 offset:6600
	ds_write_b32 v10, v178 offset:6864
	ds_write_b32 v10, v179 offset:7128
	ds_write_b32 v10, v180 offset:7392
	ds_write_b32 v10, v181 offset:7656
	ds_write_b32 v10, v182 offset:7920
	ds_write_b32 v10, v183 offset:8184
	s_cmp_eq_u32 s72, 0
	s_cbranch_scc1 .Lcv_g1B
	v_mov_b32_e32 v28, v36
	v_mov_b32_e32 v29, v37
	v_mov_b32_e32 v30, v38
	v_mov_b32_e32 v31, v39
	v_mov_b32_e32 v32, v40
	v_mov_b32_e32 v33, v41
	v_mov_b32_e32 v34, v42
	v_mov_b32_e32 v35, v43
	s_branch .Lcv_g2B

; #define LAS __attribute__((address_space(3)))
; __device__ __forceinline__ unsigned pk2(float lo, float hi) { f32x2 v = {lo, hi}; bf2_t b = __builtin_convertvector(v, bf2_t); return __builtin_bit_cast(unsigned, b); }
; __device__ __forceinline__ void transpose_item(const float* W, int K, int Nsrc, const float* gain, bf16_t* WT, int dst_row0, int src_col0, int k0, LAS float* scr, int lane) {
; #pragma unroll 8
;     for (int i = 0; i < 32; ++i) { const int kk = 2 * i + (lane >> 5); const float g = gain ? gain[k0 + kk] : 1.f; scr[kk * 33 + (lane & 31)] = W[(size_t)(k0 + kk) * Nsrc + src_col0 + (lane & 31)] * g; }
;     asm volatile("s_waitcnt lgkmcnt(0)" ::: "memory");
;     const int c = lane & 7;
; #pragma unroll
;     for (int j = 0; j < 4; ++j) { const int n = (lane >> 3) + 8 * j; const LAS float* s = scr + (8 * c) * 33 + n;
;         u32x4 o; o.x = pk2(s[0 * 33], s[1 * 33]); o.y = pk2(s[2 * 33], s[3 * 33]); o.z = pk2(s[4 * 33], s[5 * 33]); o.w = pk2(s[6 * 33], s[7 * 33]);
;         *(u32x4*)(WT + (size_t)(dst_row0 + n) * K + k0 + 8 * c) = o; }
;     asm volatile("s_waitcnt lgkmcnt(0)" ::: "memory");
.Lcvd4_hasg:
	global_load_dword v152, v14, s[8:9]
	s_add_u32 s8, s8, s10
	s_addc_u32 s9, s9, 0
	global_load_dword v153, v14, s[8:9]
	s_add_u32 s8, s8, s10
	s_addc_u32 s9, s9, 0
	global_load_dword v154, v14, s[8:9]
	s_add_u32 s8, s8, s10
	s_addc_u32 s9, s9, 0
	global_load_dword v155, v14, s[8:9]
	s_add_u32 s8, s8, s10
	s_addc_u32 s9, s9, 0
	global_load_dword v156, v14, s[8:9]
	s_add_u32 s8, s8, s10
	s_addc_u32 s9, s9, 0
	global_load_dword v157, v14, s[8:9]
	s_add_u32 s8, s8, s10
	s_addc_u32 s9, s9, 0
	global_load_dword v158, v14, s[8:9]
	s_add_u32 s8, s8, s10
	s_addc_u32 s9, s9, 0
	global_load_dword v159, v14, s[8:9]
	s_add_u32 s8, s8, s10
	s_addc_u32 s9, s9, 0
	global_load_dword v160, v14, s[8:9]
	s_add_u32 s8, s8, s10
	s_addc_u32 s9, s9, 0
	global_load_dword v161, v14, s[8:9]
	s_add_u32 s8, s8, s10
	s_addc_u32 s9, s9, 0
	global_load_dword v162, v14, s[8:9]
	s_add_u32 s8, s8, s10
	s_addc_u32 s9, s9, 0
	global_load_dword v163, v14, s[8:9]
	s_add_u32 s8, s8, s10
	s_addc_u32 s9, s9, 0
	global_load_dword v164, v14, s[8:9]
	s_add_u32 s8, s8, s10
	s_addc_u32 s9, s9, 0
	global_load_dword v165, v14, s[8:9]
	s_add_u32 s8, s8, s10
	s_addc_u32 s9, s9, 0
	global_load_dword v166, v14, s[8:9]
	s_add_u32 s8, s8, s10
	s_addc_u32 s9, s9, 0
	global_load_dword v167, v14, s[8:9]
	s_add_u32 s8, s8, s10
	s_addc_u32 s9, s9, 0
	global_load_dword v168, v14, s[8:9]
	s_add_u32 s8, s8, s10
	s_addc_u32 s9, s9, 0
	global_load_dword v169, v14, s[8:9]
	s_add_u32 s8, s8, s10
	s_addc_u32 s9, s9, 0
	global_load_dword v170, v14, s[8:9]
	s_add_u32 s8, s8, s10
	s_addc_u32 s9, s9, 0
	global_load_dword v171, v14, s[8:9]
	s_add_u32 s8, s8, s10
	s_addc_u32 s9, s9, 0
	global_load_dword v172, v14, s[8:9]
	s_add_u32 s8, s8, s10
	s_addc_u32 s9, s9, 0
	global_load_dword v173, v14, s[8:9]
	s_add_u32 s8, s8, s10
	s_addc_u32 s9, s9, 0
	global_load_dword v174, v14, s[8:9]
	s_add_u32 s8, s8, s10
	s_addc_u32 s9, s9, 0
	global_load_dword v175, v14, s[8:9]
	s_add_u32 s8, s8, s10
	s_addc_u32 s9, s9, 0
	global_load_dword v176, v14, s[8:9]
	s_add_u32 s8, s8, s10
	s_addc_u32 s9, s9, 0
	global_load_dword v177, v14, s[8:9]
	s_add_u32 s8, s8, s10
	s_addc_u32 s9, s9, 0
	global_load_dword v178, v14, s[8:9]
	s_add_u32 s8, s8, s10
	s_addc_u32 s9, s9, 0
	global_load_dword v179, v14, s[8:9]
	s_add_u32 s8, s8, s10
	s_addc_u32 s9, s9, 0
	global_load_dword v180, v14, s[8:9]
	s_add_u32 s8, s8, s10
	s_addc_u32 s9, s9, 0
	global_load_dword v181, v14, s[8:9]
	s_add_u32 s8, s8, s10
	s_addc_u32 s9, s9, 0
	global_load_dword v182, v14, s[8:9]
	s_add_u32 s8, s8, s10
	s_addc_u32 s9, s9, 0
	global_load_dword v183, v14, s[8:9]
	global_load_dwordx4 v[36:39], v12, s[12:13]
	global_load_dwordx4 v[40:43], v12, s[12:13] offset:16
.Lcv_nonextB:
	s_waitcnt lgkmcnt(0)
	ds_read_b32 v104, v11 offset:0
	ds_read_b32 v105, v11 offset:132
	ds_read_b32 v106, v11 offset:264
	ds_read_b32 v107, v11 offset:396
	ds_read_b32 v108, v11 offset:528
	ds_read_b32 v109, v11 offset:660
	ds_read_b32 v110, v11 offset:792
	ds_read_b32 v111, v11 offset:924
	ds_read_b32 v112, v11 offset:32
	ds_read_b32 v113, v11 offset:164
	ds_read_b32 v114, v11 offset:296
	ds_read_b32 v115, v11 offset:428
	ds_read_b32 v116, v11 offset:560
	ds_read_b32 v117, v11 offset:692
	ds_read_b32 v118, v11 offset:824
	ds_read_b32 v119, v11 offset:956
	s_waitcnt lgkmcnt(8)
	v_mul_f32_e32 v104, v104, v28
	v_mul_f32_e32 v105, v105, v29
	v_mul_f32_e32 v106, v106, v30
	v_mul_f32_e32 v107, v107, v31
	v_mul_f32_e32 v108, v108, v32
	v_mul_f32_e32 v109, v109, v33
	v_mul_f32_e32 v110, v110, v34
	v_mul_f32_e32 v111, v111, v35
	v_cvt_pk_bf16_f32 v136, v104, v105
	v_cvt_pk_bf16_f32 v137, v106, v107
	v_cvt_pk_bf16_f32 v138, v108, v109
	v_cvt_pk_bf16_f32 v139, v110, v111
	global_store_dwordx4 v17, v[136:139], s[52:53]
	s_add_u32 s52, s52, s58
	s_addc_u32 s53, s53, 0
	ds_read_b32 v120, v11 offset:64
	ds_read_b32 v121, v11 offset:196
	ds_read_b32 v122, v11 offset:328
	ds_read_b32 v123, v11 offset:460
	ds_read_b32 v124, v11 offset:592
	ds_read_b32 v125, v11 offset:724
	ds_read_b32 v126, v11 offset:856
	ds_read_b32 v127, v11 offset:988
	s_waitcnt lgkmcnt(8)
	v_mul_f32_e32 v112, v112, v28
	v_mul_f32_e32 v113, v113, v29
	v_mul_f32_e32 v114, v114, v30
	v_mul_f32_e32 v115, v115, v31
	v_mul_f32_e32 v116, v116, v32
	v_mul_f32_e32 v117, v117, v33
	v_mul_f32_e32 v118, v118, v34
	v_mul_f32_e32 v119, v119, v35
	v_cvt_pk_bf16_f32 v140, v112, v113
	v_cvt_pk_bf16_f32 v141, v114, v115
	v_cvt_pk_bf16_f32 v142, v116, v117
	v_cvt_pk_bf16_f32 v143, v118, v119
	global_store_dwordx4 v17, v[140:143], s[52:53]
	s_add_u32 s52, s52, s58
	s_addc_u32 s53, s53, 0
	ds_read_b32 v128, v11 offset:96
	ds_read_b32 v129, v11 offset:228
	ds_read_b32 v130, v11 offset:360
	ds_read_b32 v131, v11 offset:492
	ds_read_b32 v132, v11 offset:624
	ds_read_b32 v133, v11 offset:756
	ds_read_b32 v134, v11 offset:888
	ds_read_b32 v135, v11 offset:1020
	s_waitcnt lgkmcnt(8)
	v_mul_f32_e32 v120, v120, v28
	v_mul_f32_e32 v121, v121, v29
	v_mul_f32_e32 v122, v122, v30
	v_mul_f32_e32 v123, v123, v31
	v_mul_f32_e32 v124, v124, v32
	v_mul_f32_e32 v125, v125, v33
	v_mul_f32_e32 v126, v126, v34
	v_mul_f32_e32 v127, v127, v35
	v_cvt_pk_bf16_f32 v144, v120, v121
	v_cvt_pk_bf16_f32 v145, v122, v123
	v_cvt_pk_bf16_f32 v146, v124, v125
	v_cvt_pk_bf16_f32 v147, v126, v127
	global_store_dwordx4 v17, v[144:147], s[52:53]
	s_add_u32 s52, s52, s58
	s_addc_u32 s53, s53, 0
	s_waitcnt lgkmcnt(0)
	v_mul_f32_e32 v128, v128, v28
	v_mul_f32_e32 v129, v129, v29
	v_mul_f32_e32 v130, v130, v30
	v_mul_f32_e32 v131, v131, v31
	v_mul_f32_e32 v132, v132, v32
	v_mul_f32_e32 v133, v133, v33
	v_mul_f32_e32 v134, v134, v34
	v_mul_f32_e32 v135, v135, v35
	v_cvt_pk_bf16_f32 v148, v128, v129
	v_cvt_pk_bf16_f32 v149, v130, v131
	v_cvt_pk_bf16_f32 v150, v132, v133
	v_cvt_pk_bf16_f32 v151, v134, v135
	global_store_dwordx4 v17, v[148:151], s[52:53]
	s_mov_b64 s[52:53], s[14:15]
	s_mov_b32 s58, s16
	s_mov_b32 s72, s38
	v_mov_b32_e32 v17, v15
	s_add_u32 s30, s30, 0x800
	s_cmpk_lt_u32 s30, 0x3b00
	s_cbranch_scc1 .Lcv_bodyA
	s_branch .Lcv_end
